# grid barriers: arrival generation / leader test from the known barrier number instead of the division emulation
# baseline (speedup 1.0000x reference)
; DI unsigned xb_ld(unsigned* p)              { return __hip_atomic_load(p, __ATOMIC_RELAXED, __HIP_MEMORY_SCOPE_AGENT); }
; DI unsigned xb_add(unsigned* p, unsigned v) { return __hip_atomic_fetch_add(p, v, __ATOMIC_RELAXED, __HIP_MEMORY_SCOPE_AGENT); }
; #define XB_SPIN(cond, bar) do { unsigned _sp = 0; while (cond) { __builtin_amdgcn_s_sleep(1); \
;     if ((++_sp & 255u) == 0u) { if (xb_ld(&(bar)[XB_TMO])) break; if (_sp > XB_SPIN_CAP) { atomicAdd(&(bar)[XB_TMO], 1u); break; } } } } while (0)
; DI void xcd_barrier(unsigned* bar, volatile __attribute__((address_space(3))) unsigned* st) {
;     ...
;         const unsigned old = xb_add(&bar[XB_XSUB(x)], 1u);
;         const unsigned gen = old / nloc;
;         if (old + 1u == (gen + 1u) * nloc) {
;             __builtin_amdgcn_fence(__ATOMIC_RELEASE, "agent");
;             asm volatile("s_waitcnt vmcnt(0)" ::: "memory");
;             const unsigned og = xb_add(&bar[XB_TOP], 1u);
;             const unsigned tg = og / nx;
;             if (og + 1u == (tg + 1u) * nx) xb_add(&bar[XB_TOPGEN], 1u);
;             else XB_SPIN(xb_ld(&bar[XB_TOPGEN]) == tg, bar);
;             __builtin_amdgcn_fence(__ATOMIC_ACQUIRE, "agent");
;             xb_add(&bar[XB_XGEN(x)], 1u);
;             asm volatile("s_waitcnt vmcnt(0)" ::: "memory");
;         } else {
;             XB_SPIN(xb_ld(&bar[XB_XGEN(x)]) == gen, bar);
.LBB0_150:
	s_or_b64 exec, exec, s[8:9]
	s_waitcnt vmcnt(0)
	v_readfirstlane_b32 s3, v3
	v_mul_u32_u24_e32 v2, 1, v2
	v_add_u32_e32 v5, s3, v0
	v_mov_b32_e32 v0, 0
	v_add_u32_e32 v3, 1, v5
	v_cmp_ne_u32_e32 vcc, v3, v2
	s_and_saveexec_b64 s[6:7], vcc
	s_xor_b64 s[6:7], exec, s[6:7]
	s_cbranch_execz .LBB0_164
	buffer_inv sc1
	s_waitcnt lgkmcnt(0)
	v_mov_b32_e32 v1, 0x2000
	global_load_dword v1, v1, s[4:5] offset:1024 sc1
	s_add_u32 s12, s4, 0x2400
	s_addc_u32 s13, s5, 0
	s_waitcnt vmcnt(0)
	v_cmp_eq_u32_e32 vcc, v1, v0
	s_and_saveexec_b64 s[8:9], vcc
	s_cbranch_execz .LBB0_163
	s_add_u32 s10, s70, 0x34e2300
	s_addc_u32 s11, s71, 0
	s_mov_b32 s3, 1
	s_mov_b64 s[14:15], 0
	v_mov_b32_e32 v1, 0
	s_branch .LBB0_154

; DI unsigned xb_ld(unsigned* p)              { return __hip_atomic_load(p, __ATOMIC_RELAXED, __HIP_MEMORY_SCOPE_AGENT); }
; DI unsigned xb_add(unsigned* p, unsigned v) { return __hip_atomic_fetch_add(p, v, __ATOMIC_RELAXED, __HIP_MEMORY_SCOPE_AGENT); }
; #define XB_SPIN(cond, bar) do { unsigned _sp = 0; while (cond) { __builtin_amdgcn_s_sleep(1); \
;     if ((++_sp & 255u) == 0u) { if (xb_ld(&(bar)[XB_TMO])) break; if (_sp > XB_SPIN_CAP) { atomicAdd(&(bar)[XB_TMO], 1u); break; } } } } while (0)
; DI void xcd_barrier(unsigned* bar, volatile __attribute__((address_space(3))) unsigned* st) {
;     ...
;         const unsigned old = xb_add(&bar[XB_XSUB(x)], 1u);
;         const unsigned gen = old / nloc;
;         if (old + 1u == (gen + 1u) * nloc) {
;             __builtin_amdgcn_fence(__ATOMIC_RELEASE, "agent");
;             asm volatile("s_waitcnt vmcnt(0)" ::: "memory");
;             const unsigned og = xb_add(&bar[XB_TOP], 1u);
;             const unsigned tg = og / nx;
;             if (og + 1u == (tg + 1u) * nx) xb_add(&bar[XB_TOPGEN], 1u);
;             else XB_SPIN(xb_ld(&bar[XB_TOPGEN]) == tg, bar);
;             __builtin_amdgcn_fence(__ATOMIC_ACQUIRE, "agent");
;             xb_add(&bar[XB_XGEN(x)], 1u);
;             asm volatile("s_waitcnt vmcnt(0)" ::: "memory");
;         } else {
;             XB_SPIN(xb_ld(&bar[XB_XGEN(x)]) == gen, bar);
.LBB0_240:
	s_or_b64 exec, exec, s[10:11]
	s_waitcnt vmcnt(0)
	v_readfirstlane_b32 s3, v3
	v_mul_u32_u24_e32 v2, 2, v2
	v_add_u32_e32 v5, s3, v0
	v_mov_b32_e32 v0, 1
	v_add_u32_e32 v3, 1, v5
	v_cmp_ne_u32_e32 vcc, v3, v2
	s_and_saveexec_b64 s[8:9], vcc
	s_xor_b64 s[8:9], exec, s[8:9]
	s_cbranch_execz .LBB0_254
	buffer_inv sc1
	s_waitcnt lgkmcnt(0)
	v_mov_b32_e32 v1, 0x2000
	global_load_dword v1, v1, s[6:7] offset:1024 sc1
	s_add_u32 s14, s6, 0x2400
	s_addc_u32 s15, s7, 0
	s_waitcnt vmcnt(0)
	v_cmp_eq_u32_e32 vcc, v1, v0
	s_and_saveexec_b64 s[10:11], vcc
	s_cbranch_execz .LBB0_253
	s_add_u32 s12, s70, 0x34e2300
	s_addc_u32 s13, s71, 0
	s_mov_b32 s3, 1
	s_mov_b64 s[16:17], 0
	v_mov_b32_e32 v1, 0
	s_branch .LBB0_244

; DI unsigned xb_ld(unsigned* p)              { return __hip_atomic_load(p, __ATOMIC_RELAXED, __HIP_MEMORY_SCOPE_AGENT); }
; DI unsigned xb_add(unsigned* p, unsigned v) { return __hip_atomic_fetch_add(p, v, __ATOMIC_RELAXED, __HIP_MEMORY_SCOPE_AGENT); }
; #define XB_SPIN(cond, bar) do { unsigned _sp = 0; while (cond) { __builtin_amdgcn_s_sleep(1); \
;     if ((++_sp & 255u) == 0u) { if (xb_ld(&(bar)[XB_TMO])) break; if (_sp > XB_SPIN_CAP) { atomicAdd(&(bar)[XB_TMO], 1u); break; } } } } while (0)
; DI void xcd_barrier(unsigned* bar, volatile __attribute__((address_space(3))) unsigned* st) {
;     ...
;         const unsigned old = xb_add(&bar[XB_XSUB(x)], 1u);
;         const unsigned gen = old / nloc;
;         if (old + 1u == (gen + 1u) * nloc) {
;             __builtin_amdgcn_fence(__ATOMIC_RELEASE, "agent");
;             asm volatile("s_waitcnt vmcnt(0)" ::: "memory");
;             const unsigned og = xb_add(&bar[XB_TOP], 1u);
;             const unsigned tg = og / nx;
;             if (og + 1u == (tg + 1u) * nx) xb_add(&bar[XB_TOPGEN], 1u);
;             else XB_SPIN(xb_ld(&bar[XB_TOPGEN]) == tg, bar);
;             __builtin_amdgcn_fence(__ATOMIC_ACQUIRE, "agent");
;             xb_add(&bar[XB_XGEN(x)], 1u);
;             asm volatile("s_waitcnt vmcnt(0)" ::: "memory");
;         } else {
;             XB_SPIN(xb_ld(&bar[XB_XGEN(x)]) == gen, bar);
.LBB0_323:
	s_or_b64 exec, exec, s[10:11]
	s_waitcnt vmcnt(0)
	v_readfirstlane_b32 s3, v3
	v_mul_u32_u24_e32 v2, 3, v2
	v_add_u32_e32 v5, s3, v0
	v_mov_b32_e32 v0, 2
	v_add_u32_e32 v3, 1, v5
	v_cmp_ne_u32_e32 vcc, v3, v2
	s_and_saveexec_b64 s[8:9], vcc
	s_xor_b64 s[8:9], exec, s[8:9]
	s_cbranch_execz .LBB0_337
	buffer_inv sc1
	s_waitcnt lgkmcnt(0)
	v_mov_b32_e32 v1, 0x2000
	global_load_dword v1, v1, s[6:7] offset:1024 sc1
	s_add_u32 s14, s6, 0x2400
	s_addc_u32 s15, s7, 0
	s_waitcnt vmcnt(0)
	v_cmp_eq_u32_e32 vcc, v1, v0
	s_and_saveexec_b64 s[10:11], vcc
	s_cbranch_execz .LBB0_336
	s_add_u32 s12, s70, 0x34e2300
	s_addc_u32 s13, s71, 0
	s_mov_b32 s3, 1
	s_mov_b64 s[16:17], 0
	v_mov_b32_e32 v1, 0
	s_branch .LBB0_327

; DI unsigned xb_ld(unsigned* p)              { return __hip_atomic_load(p, __ATOMIC_RELAXED, __HIP_MEMORY_SCOPE_AGENT); }
; DI unsigned xb_add(unsigned* p, unsigned v) { return __hip_atomic_fetch_add(p, v, __ATOMIC_RELAXED, __HIP_MEMORY_SCOPE_AGENT); }
; #define XB_SPIN(cond, bar) do { unsigned _sp = 0; while (cond) { __builtin_amdgcn_s_sleep(1); \
;     if ((++_sp & 255u) == 0u) { if (xb_ld(&(bar)[XB_TMO])) break; if (_sp > XB_SPIN_CAP) { atomicAdd(&(bar)[XB_TMO], 1u); break; } } } } while (0)
; DI void xcd_barrier(unsigned* bar, volatile __attribute__((address_space(3))) unsigned* st) {
;     ...
;         const unsigned old = xb_add(&bar[XB_XSUB(x)], 1u);
;         const unsigned gen = old / nloc;
;         if (old + 1u == (gen + 1u) * nloc) {
;             __builtin_amdgcn_fence(__ATOMIC_RELEASE, "agent");
;             asm volatile("s_waitcnt vmcnt(0)" ::: "memory");
;             const unsigned og = xb_add(&bar[XB_TOP], 1u);
;             const unsigned tg = og / nx;
;             if (og + 1u == (tg + 1u) * nx) xb_add(&bar[XB_TOPGEN], 1u);
;             else XB_SPIN(xb_ld(&bar[XB_TOPGEN]) == tg, bar);
;             __builtin_amdgcn_fence(__ATOMIC_ACQUIRE, "agent");
;             xb_add(&bar[XB_XGEN(x)], 1u);
;             asm volatile("s_waitcnt vmcnt(0)" ::: "memory");
;         } else {
;             XB_SPIN(xb_ld(&bar[XB_XGEN(x)]) == gen, bar);
.LBB0_400:
	s_or_b64 exec, exec, s[8:9]
	s_waitcnt vmcnt(0)
	v_readfirstlane_b32 s3, v3
	v_mul_u32_u24_e32 v2, 4, v2
	v_add_u32_e32 v5, s3, v0
	v_mov_b32_e32 v0, 3
	v_add_u32_e32 v3, 1, v5
	v_cmp_ne_u32_e32 vcc, v3, v2
	s_and_saveexec_b64 s[6:7], vcc
	s_xor_b64 s[6:7], exec, s[6:7]
	s_cbranch_execz .LBB0_414
	buffer_inv sc1
	s_waitcnt lgkmcnt(0)
	v_mov_b32_e32 v1, 0x2000
	global_load_dword v1, v1, s[4:5] offset:1024 sc1
	s_add_u32 s12, s4, 0x2400
	s_addc_u32 s13, s5, 0
	s_waitcnt vmcnt(0)
	v_cmp_eq_u32_e32 vcc, v1, v0
	s_and_saveexec_b64 s[8:9], vcc
	s_cbranch_execz .LBB0_413
	s_add_u32 s10, s70, 0x34e2300
	s_addc_u32 s11, s71, 0
	s_mov_b32 s3, 1
	s_mov_b64 s[16:17], 0
	v_mov_b32_e32 v1, 0
	s_branch .LBB0_404

; DI unsigned xb_ld(unsigned* p)              { return __hip_atomic_load(p, __ATOMIC_RELAXED, __HIP_MEMORY_SCOPE_AGENT); }
; DI unsigned xb_add(unsigned* p, unsigned v) { return __hip_atomic_fetch_add(p, v, __ATOMIC_RELAXED, __HIP_MEMORY_SCOPE_AGENT); }
; #define XB_SPIN(cond, bar) do { unsigned _sp = 0; while (cond) { __builtin_amdgcn_s_sleep(1); \
;     if ((++_sp & 255u) == 0u) { if (xb_ld(&(bar)[XB_TMO])) break; if (_sp > XB_SPIN_CAP) { atomicAdd(&(bar)[XB_TMO], 1u); break; } } } } while (0)
; DI void xcd_barrier(unsigned* bar, volatile __attribute__((address_space(3))) unsigned* st) {
;     ...
;         const unsigned old = xb_add(&bar[XB_XSUB(x)], 1u);
;         const unsigned gen = old / nloc;
;         if (old + 1u == (gen + 1u) * nloc) {
;             __builtin_amdgcn_fence(__ATOMIC_RELEASE, "agent");
;             asm volatile("s_waitcnt vmcnt(0)" ::: "memory");
;             const unsigned og = xb_add(&bar[XB_TOP], 1u);
;             const unsigned tg = og / nx;
;             if (og + 1u == (tg + 1u) * nx) xb_add(&bar[XB_TOPGEN], 1u);
;             else XB_SPIN(xb_ld(&bar[XB_TOPGEN]) == tg, bar);
;             __builtin_amdgcn_fence(__ATOMIC_ACQUIRE, "agent");
;             xb_add(&bar[XB_XGEN(x)], 1u);
;             asm volatile("s_waitcnt vmcnt(0)" ::: "memory");
;         } else {
;             XB_SPIN(xb_ld(&bar[XB_XGEN(x)]) == gen, bar);
.LBB0_490:
	s_or_b64 exec, exec, s[10:11]
	s_waitcnt vmcnt(0)
	v_readfirstlane_b32 s3, v3
	v_mul_u32_u24_e32 v2, 5, v2
	v_add_u32_e32 v5, s3, v0
	v_mov_b32_e32 v0, 4
	v_add_u32_e32 v3, 1, v5
	v_cmp_ne_u32_e32 vcc, v3, v2
	s_and_saveexec_b64 s[8:9], vcc
	s_xor_b64 s[8:9], exec, s[8:9]
	s_cbranch_execz .LBB0_504
	buffer_inv sc1
	s_waitcnt lgkmcnt(0)
	v_mov_b32_e32 v1, 0x2000
	global_load_dword v1, v1, s[4:5] offset:1024 sc1
	s_add_u32 s14, s4, 0x2400
	s_addc_u32 s15, s5, 0
	s_waitcnt vmcnt(0)
	v_cmp_eq_u32_e32 vcc, v1, v0
	s_and_saveexec_b64 s[10:11], vcc
	s_cbranch_execz .LBB0_503
	s_add_u32 s12, s70, 0x34e2300
	s_addc_u32 s13, s71, 0
	s_mov_b32 s3, 1
	s_mov_b64 s[16:17], 0
	v_mov_b32_e32 v1, 0
	s_branch .LBB0_494

; DI unsigned xb_ld(unsigned* p)              { return __hip_atomic_load(p, __ATOMIC_RELAXED, __HIP_MEMORY_SCOPE_AGENT); }
; DI unsigned xb_add(unsigned* p, unsigned v) { return __hip_atomic_fetch_add(p, v, __ATOMIC_RELAXED, __HIP_MEMORY_SCOPE_AGENT); }
; #define XB_SPIN(cond, bar) do { unsigned _sp = 0; while (cond) { __builtin_amdgcn_s_sleep(1); \
;     if ((++_sp & 255u) == 0u) { if (xb_ld(&(bar)[XB_TMO])) break; if (_sp > XB_SPIN_CAP) { atomicAdd(&(bar)[XB_TMO], 1u); break; } } } } while (0)
; DI void xcd_barrier(unsigned* bar, volatile __attribute__((address_space(3))) unsigned* st) {
;     ...
;         const unsigned old = xb_add(&bar[XB_XSUB(x)], 1u);
;         const unsigned gen = old / nloc;
;         if (old + 1u == (gen + 1u) * nloc) {
;             __builtin_amdgcn_fence(__ATOMIC_RELEASE, "agent");
;             asm volatile("s_waitcnt vmcnt(0)" ::: "memory");
;             const unsigned og = xb_add(&bar[XB_TOP], 1u);
;             const unsigned tg = og / nx;
;             if (og + 1u == (tg + 1u) * nx) xb_add(&bar[XB_TOPGEN], 1u);
;             else XB_SPIN(xb_ld(&bar[XB_TOPGEN]) == tg, bar);
;             __builtin_amdgcn_fence(__ATOMIC_ACQUIRE, "agent");
;             xb_add(&bar[XB_XGEN(x)], 1u);
;             asm volatile("s_waitcnt vmcnt(0)" ::: "memory");
;         } else {
;             XB_SPIN(xb_ld(&bar[XB_XGEN(x)]) == gen, bar);
.LBB0_598:
	s_or_b64 exec, exec, s[8:9]
	s_waitcnt vmcnt(0)
	v_readfirstlane_b32 s3, v3
	v_mul_u32_u24_e32 v2, 6, v2
	v_add_u32_e32 v5, s3, v0
	v_mov_b32_e32 v0, 5
	v_add_u32_e32 v3, 1, v5
	v_cmp_ne_u32_e32 vcc, v3, v2
	s_and_saveexec_b64 s[6:7], vcc
	s_xor_b64 s[6:7], exec, s[6:7]
	s_cbranch_execz .LBB0_612
	buffer_inv sc1
	s_waitcnt lgkmcnt(0)
	v_mov_b32_e32 v1, 0x2000
	global_load_dword v1, v1, s[4:5] offset:1024 sc1
	s_add_u32 s12, s4, 0x2400
	s_addc_u32 s13, s5, 0
	s_waitcnt vmcnt(0)
	v_cmp_eq_u32_e32 vcc, v1, v0
	s_and_saveexec_b64 s[8:9], vcc
	s_cbranch_execz .LBB0_611
	s_add_u32 s10, s70, 0x34e2300
	s_addc_u32 s11, s71, 0
	s_mov_b32 s3, 1
	s_mov_b64 s[14:15], 0
	v_mov_b32_e32 v1, 0
	s_branch .LBB0_602

; DI unsigned xb_ld(unsigned* p)              { return __hip_atomic_load(p, __ATOMIC_RELAXED, __HIP_MEMORY_SCOPE_AGENT); }
; DI unsigned xb_add(unsigned* p, unsigned v) { return __hip_atomic_fetch_add(p, v, __ATOMIC_RELAXED, __HIP_MEMORY_SCOPE_AGENT); }
; #define XB_SPIN(cond, bar) do { unsigned _sp = 0; while (cond) { __builtin_amdgcn_s_sleep(1); \
;     if ((++_sp & 255u) == 0u) { if (xb_ld(&(bar)[XB_TMO])) break; if (_sp > XB_SPIN_CAP) { atomicAdd(&(bar)[XB_TMO], 1u); break; } } } } while (0)
; DI void xcd_barrier(unsigned* bar, volatile __attribute__((address_space(3))) unsigned* st) {
;     ...
;         const unsigned old = xb_add(&bar[XB_XSUB(x)], 1u);
;         const unsigned gen = old / nloc;
;         if (old + 1u == (gen + 1u) * nloc) {
;             __builtin_amdgcn_fence(__ATOMIC_RELEASE, "agent");
;             asm volatile("s_waitcnt vmcnt(0)" ::: "memory");
;             const unsigned og = xb_add(&bar[XB_TOP], 1u);
;             const unsigned tg = og / nx;
;             if (og + 1u == (tg + 1u) * nx) xb_add(&bar[XB_TOPGEN], 1u);
;             else XB_SPIN(xb_ld(&bar[XB_TOPGEN]) == tg, bar);
;             __builtin_amdgcn_fence(__ATOMIC_ACQUIRE, "agent");
;             xb_add(&bar[XB_XGEN(x)], 1u);
;             asm volatile("s_waitcnt vmcnt(0)" ::: "memory");
;         } else {
;             XB_SPIN(xb_ld(&bar[XB_XGEN(x)]) == gen, bar);
.LBB0_680:
	s_or_b64 exec, exec, s[8:9]
	s_waitcnt vmcnt(0)
	v_readfirstlane_b32 s3, v3
	v_mul_u32_u24_e32 v2, 7, v2
	v_add_u32_e32 v5, s3, v0
	v_mov_b32_e32 v0, 6
	v_add_u32_e32 v3, 1, v5
	v_cmp_ne_u32_e32 vcc, v3, v2
	s_and_saveexec_b64 s[6:7], vcc
	s_xor_b64 s[6:7], exec, s[6:7]
	s_cbranch_execz .LBB0_694
	buffer_inv sc1
	s_waitcnt lgkmcnt(0)
	v_mov_b32_e32 v1, 0x2000
	global_load_dword v1, v1, s[4:5] offset:1024 sc1
	s_add_u32 s12, s4, 0x2400
	s_addc_u32 s13, s5, 0
	s_waitcnt vmcnt(0)
	v_cmp_eq_u32_e32 vcc, v1, v0
	s_and_saveexec_b64 s[8:9], vcc
	s_cbranch_execz .LBB0_693
	s_add_u32 s10, s70, 0x34e2300
	s_addc_u32 s11, s71, 0
	s_mov_b32 s3, 1
	s_mov_b64 s[14:15], 0
	v_mov_b32_e32 v1, 0
	s_branch .LBB0_684

; DI unsigned xb_ld(unsigned* p)              { return __hip_atomic_load(p, __ATOMIC_RELAXED, __HIP_MEMORY_SCOPE_AGENT); }
; DI unsigned xb_add(unsigned* p, unsigned v) { return __hip_atomic_fetch_add(p, v, __ATOMIC_RELAXED, __HIP_MEMORY_SCOPE_AGENT); }
; #define XB_SPIN(cond, bar) do { unsigned _sp = 0; while (cond) { __builtin_amdgcn_s_sleep(1); \
;     if ((++_sp & 255u) == 0u) { if (xb_ld(&(bar)[XB_TMO])) break; if (_sp > XB_SPIN_CAP) { atomicAdd(&(bar)[XB_TMO], 1u); break; } } } } while (0)
; DI void xcd_barrier(unsigned* bar, volatile __attribute__((address_space(3))) unsigned* st) {
;     ...
;         const unsigned old = xb_add(&bar[XB_XSUB(x)], 1u);
;         const unsigned gen = old / nloc;
;         if (old + 1u == (gen + 1u) * nloc) {
;             __builtin_amdgcn_fence(__ATOMIC_RELEASE, "agent");
;             asm volatile("s_waitcnt vmcnt(0)" ::: "memory");
;             const unsigned og = xb_add(&bar[XB_TOP], 1u);
;             const unsigned tg = og / nx;
;             if (og + 1u == (tg + 1u) * nx) xb_add(&bar[XB_TOPGEN], 1u);
;             else XB_SPIN(xb_ld(&bar[XB_TOPGEN]) == tg, bar);
;             __builtin_amdgcn_fence(__ATOMIC_ACQUIRE, "agent");
;             xb_add(&bar[XB_XGEN(x)], 1u);
;             asm volatile("s_waitcnt vmcnt(0)" ::: "memory");
;         } else {
;             XB_SPIN(xb_ld(&bar[XB_XGEN(x)]) == gen, bar);
.LBB0_801:
	s_or_b64 exec, exec, s[8:9]
	s_waitcnt vmcnt(0)
	v_readfirstlane_b32 s3, v3
	v_mul_u32_u24_e32 v2, 8, v2
	v_add_u32_e32 v5, s3, v0
	v_mov_b32_e32 v0, 7
	v_add_u32_e32 v3, 1, v5
	v_cmp_ne_u32_e32 vcc, v3, v2
	s_and_saveexec_b64 s[6:7], vcc
	s_xor_b64 s[6:7], exec, s[6:7]
	s_cbranch_execz .LBB0_815
	buffer_inv sc1
	s_waitcnt lgkmcnt(0)
	v_mov_b32_e32 v1, 0x2000
	global_load_dword v1, v1, s[4:5] offset:1024 sc1
	s_add_u32 s12, s4, 0x2400
	s_addc_u32 s13, s5, 0
	s_waitcnt vmcnt(0)
	v_cmp_eq_u32_e32 vcc, v1, v0
	s_and_saveexec_b64 s[8:9], vcc
	s_cbranch_execz .LBB0_814
	s_add_u32 s10, s70, 0x34e2300
	s_addc_u32 s11, s71, 0
	s_mov_b32 s3, 1
	s_mov_b64 s[14:15], 0
	v_mov_b32_e32 v1, 0
	s_branch .LBB0_805

; DI unsigned xb_ld(unsigned* p)              { return __hip_atomic_load(p, __ATOMIC_RELAXED, __HIP_MEMORY_SCOPE_AGENT); }
; DI unsigned xb_add(unsigned* p, unsigned v) { return __hip_atomic_fetch_add(p, v, __ATOMIC_RELAXED, __HIP_MEMORY_SCOPE_AGENT); }
; #define XB_SPIN(cond, bar) do { unsigned _sp = 0; while (cond) { __builtin_amdgcn_s_sleep(1); \
;     if ((++_sp & 255u) == 0u) { if (xb_ld(&(bar)[XB_TMO])) break; if (_sp > XB_SPIN_CAP) { atomicAdd(&(bar)[XB_TMO], 1u); break; } } } } while (0)
; DI void xcd_barrier(unsigned* bar, volatile __attribute__((address_space(3))) unsigned* st) {
;     ...
;         const unsigned old = xb_add(&bar[XB_XSUB(x)], 1u);
;         const unsigned gen = old / nloc;
;         if (old + 1u == (gen + 1u) * nloc) {
;             __builtin_amdgcn_fence(__ATOMIC_RELEASE, "agent");
;             asm volatile("s_waitcnt vmcnt(0)" ::: "memory");
;             const unsigned og = xb_add(&bar[XB_TOP], 1u);
;             const unsigned tg = og / nx;
;             if (og + 1u == (tg + 1u) * nx) xb_add(&bar[XB_TOPGEN], 1u);
;             else XB_SPIN(xb_ld(&bar[XB_TOPGEN]) == tg, bar);
;             __builtin_amdgcn_fence(__ATOMIC_ACQUIRE, "agent");
;             xb_add(&bar[XB_XGEN(x)], 1u);
;             asm volatile("s_waitcnt vmcnt(0)" ::: "memory");
;         } else {
;             XB_SPIN(xb_ld(&bar[XB_XGEN(x)]) == gen, bar);
.LBB0_877:
	s_or_b64 exec, exec, s[10:11]
	s_waitcnt vmcnt(0)
	v_readfirstlane_b32 s3, v3
	v_mul_u32_u24_e32 v2, 9, v2
	v_add_u32_e32 v5, s3, v0
	v_mov_b32_e32 v0, 8
	v_add_u32_e32 v3, 1, v5
	v_cmp_ne_u32_e32 vcc, v3, v2
	s_and_saveexec_b64 s[8:9], vcc
	s_xor_b64 s[8:9], exec, s[8:9]
	s_cbranch_execz .LBB0_891
	buffer_inv sc1
	s_waitcnt lgkmcnt(0)
	v_mov_b32_e32 v1, 0x2000
	global_load_dword v1, v1, s[6:7] offset:1024 sc1
	s_add_u32 s14, s6, 0x2400
	s_addc_u32 s15, s7, 0
	s_waitcnt vmcnt(0)
	v_cmp_eq_u32_e32 vcc, v1, v0
	s_and_saveexec_b64 s[10:11], vcc
	s_cbranch_execz .LBB0_890
	s_add_u32 s12, s70, 0x34e2300
	s_addc_u32 s13, s71, 0
	s_mov_b32 s3, 1
	s_mov_b64 s[16:17], 0
	v_mov_b32_e32 v1, 0
	s_branch .LBB0_881

; DI unsigned xb_ld(unsigned* p)              { return __hip_atomic_load(p, __ATOMIC_RELAXED, __HIP_MEMORY_SCOPE_AGENT); }
; DI unsigned xb_add(unsigned* p, unsigned v) { return __hip_atomic_fetch_add(p, v, __ATOMIC_RELAXED, __HIP_MEMORY_SCOPE_AGENT); }
; #define XB_SPIN(cond, bar) do { unsigned _sp = 0; while (cond) { __builtin_amdgcn_s_sleep(1); \
;     if ((++_sp & 255u) == 0u) { if (xb_ld(&(bar)[XB_TMO])) break; if (_sp > XB_SPIN_CAP) { atomicAdd(&(bar)[XB_TMO], 1u); break; } } } } while (0)
; DI void xcd_barrier(unsigned* bar, volatile __attribute__((address_space(3))) unsigned* st) {
;     ...
;         const unsigned old = xb_add(&bar[XB_XSUB(x)], 1u);
;         const unsigned gen = old / nloc;
;         if (old + 1u == (gen + 1u) * nloc) {
;             __builtin_amdgcn_fence(__ATOMIC_RELEASE, "agent");
;             asm volatile("s_waitcnt vmcnt(0)" ::: "memory");
;             const unsigned og = xb_add(&bar[XB_TOP], 1u);
;             const unsigned tg = og / nx;
;             if (og + 1u == (tg + 1u) * nx) xb_add(&bar[XB_TOPGEN], 1u);
;             else XB_SPIN(xb_ld(&bar[XB_TOPGEN]) == tg, bar);
;             __builtin_amdgcn_fence(__ATOMIC_ACQUIRE, "agent");
;             xb_add(&bar[XB_XGEN(x)], 1u);
;             asm volatile("s_waitcnt vmcnt(0)" ::: "memory");
;         } else {
;             XB_SPIN(xb_ld(&bar[XB_XGEN(x)]) == gen, bar);
.LBB0_953:
	s_or_b64 exec, exec, s[10:11]
	s_waitcnt vmcnt(0)
	v_readfirstlane_b32 s3, v3
	v_mul_u32_u24_e32 v2, 10, v2
	v_add_u32_e32 v5, s3, v0
	v_mov_b32_e32 v0, 9
	v_add_u32_e32 v3, 1, v5
	v_cmp_ne_u32_e32 vcc, v3, v2
	s_and_saveexec_b64 s[8:9], vcc
	s_xor_b64 s[8:9], exec, s[8:9]
	s_cbranch_execz .LBB0_967
	buffer_inv sc1
	s_waitcnt lgkmcnt(0)
	v_mov_b32_e32 v1, 0x2000
	global_load_dword v1, v1, s[6:7] offset:1024 sc1
	s_add_u32 s14, s6, 0x2400
	s_addc_u32 s15, s7, 0
	s_waitcnt vmcnt(0)
	v_cmp_eq_u32_e32 vcc, v1, v0
	s_and_saveexec_b64 s[10:11], vcc
	s_cbranch_execz .LBB0_966
	s_add_u32 s12, s70, 0x34e2300
	s_addc_u32 s13, s71, 0
	s_mov_b32 s3, 1
	s_mov_b64 s[16:17], 0
	v_mov_b32_e32 v1, 0
	s_branch .LBB0_957

; DI unsigned xb_ld(unsigned* p)              { return __hip_atomic_load(p, __ATOMIC_RELAXED, __HIP_MEMORY_SCOPE_AGENT); }
; DI unsigned xb_add(unsigned* p, unsigned v) { return __hip_atomic_fetch_add(p, v, __ATOMIC_RELAXED, __HIP_MEMORY_SCOPE_AGENT); }
; #define XB_SPIN(cond, bar) do { unsigned _sp = 0; while (cond) { __builtin_amdgcn_s_sleep(1); \
;     if ((++_sp & 255u) == 0u) { if (xb_ld(&(bar)[XB_TMO])) break; if (_sp > XB_SPIN_CAP) { atomicAdd(&(bar)[XB_TMO], 1u); break; } } } } while (0)
; DI void xcd_barrier(unsigned* bar, volatile __attribute__((address_space(3))) unsigned* st) {
;     ...
;         const unsigned old = xb_add(&bar[XB_XSUB(x)], 1u);
;         const unsigned gen = old / nloc;
;         if (old + 1u == (gen + 1u) * nloc) {
;             __builtin_amdgcn_fence(__ATOMIC_RELEASE, "agent");
;             asm volatile("s_waitcnt vmcnt(0)" ::: "memory");
;             const unsigned og = xb_add(&bar[XB_TOP], 1u);
;             const unsigned tg = og / nx;
;             if (og + 1u == (tg + 1u) * nx) xb_add(&bar[XB_TOPGEN], 1u);
;             else XB_SPIN(xb_ld(&bar[XB_TOPGEN]) == tg, bar);
;             __builtin_amdgcn_fence(__ATOMIC_ACQUIRE, "agent");
;             xb_add(&bar[XB_XGEN(x)], 1u);
;             asm volatile("s_waitcnt vmcnt(0)" ::: "memory");
;         } else {
;             XB_SPIN(xb_ld(&bar[XB_XGEN(x)]) == gen, bar);
.LBB0_1016:
	s_or_b64 exec, exec, s[12:13]
	s_waitcnt vmcnt(0)
	v_readfirstlane_b32 s3, v3
	v_mul_u32_u24_e32 v2, 11, v2
	v_add_u32_e32 v5, s3, v0
	v_mov_b32_e32 v0, 10
	v_add_u32_e32 v3, 1, v5
	v_cmp_ne_u32_e32 vcc, v3, v2
	s_and_saveexec_b64 s[8:9], vcc
	s_xor_b64 s[8:9], exec, s[8:9]
	s_cbranch_execz .LBB0_1030
	buffer_inv sc1
	s_waitcnt lgkmcnt(0)
	v_mov_b32_e32 v1, 0x2000
	global_load_dword v1, v1, s[6:7] offset:1024 sc1
	s_add_u32 s16, s6, 0x2400
	s_addc_u32 s17, s7, 0
	s_waitcnt vmcnt(0)
	v_cmp_eq_u32_e32 vcc, v1, v0
	s_and_saveexec_b64 s[12:13], vcc
	s_cbranch_execz .LBB0_1029
	s_add_u32 s14, s70, 0x34e2300
	s_addc_u32 s15, s71, 0
	s_mov_b32 s3, 1
	s_mov_b64 s[18:19], 0
	v_mov_b32_e32 v1, 0
	s_branch .LBB0_1020

; DI unsigned xb_ld(unsigned* p)              { return __hip_atomic_load(p, __ATOMIC_RELAXED, __HIP_MEMORY_SCOPE_AGENT); }
; DI unsigned xb_add(unsigned* p, unsigned v) { return __hip_atomic_fetch_add(p, v, __ATOMIC_RELAXED, __HIP_MEMORY_SCOPE_AGENT); }
; #define XB_SPIN(cond, bar) do { unsigned _sp = 0; while (cond) { __builtin_amdgcn_s_sleep(1); \
;     if ((++_sp & 255u) == 0u) { if (xb_ld(&(bar)[XB_TMO])) break; if (_sp > XB_SPIN_CAP) { atomicAdd(&(bar)[XB_TMO], 1u); break; } } } } while (0)
; DI void xcd_barrier(unsigned* bar, volatile __attribute__((address_space(3))) unsigned* st) {
;     ...
;         const unsigned old = xb_add(&bar[XB_XSUB(x)], 1u);
;         const unsigned gen = old / nloc;
;         if (old + 1u == (gen + 1u) * nloc) {
;             __builtin_amdgcn_fence(__ATOMIC_RELEASE, "agent");
;             asm volatile("s_waitcnt vmcnt(0)" ::: "memory");
;             const unsigned og = xb_add(&bar[XB_TOP], 1u);
;             const unsigned tg = og / nx;
;             if (og + 1u == (tg + 1u) * nx) xb_add(&bar[XB_TOPGEN], 1u);
;             else XB_SPIN(xb_ld(&bar[XB_TOPGEN]) == tg, bar);
;             __builtin_amdgcn_fence(__ATOMIC_ACQUIRE, "agent");
;             xb_add(&bar[XB_XGEN(x)], 1u);
;             asm volatile("s_waitcnt vmcnt(0)" ::: "memory");
;         } else {
;             XB_SPIN(xb_ld(&bar[XB_XGEN(x)]) == gen, bar);
.LBB0_1110:
	s_or_b64 exec, exec, s[16:17]
	s_waitcnt vmcnt(0)
	v_readfirstlane_b32 s3, v3
	v_mul_u32_u24_e32 v2, 12, v2
	v_add_u32_e32 v5, s3, v0
	v_mov_b32_e32 v0, 11
	v_add_u32_e32 v3, 1, v5
	v_cmp_ne_u32_e32 vcc, v3, v2
	s_and_saveexec_b64 s[8:9], vcc
	s_xor_b64 s[8:9], exec, s[8:9]
	s_cbranch_execz .LBB0_1124
	buffer_inv sc1
	s_waitcnt lgkmcnt(0)
	v_mov_b32_e32 v1, 0x2000
	global_load_dword v1, v1, s[6:7] offset:1024 sc1
	s_add_u32 s20, s6, 0x2400
	s_addc_u32 s21, s7, 0
	s_waitcnt vmcnt(0)
	v_cmp_eq_u32_e32 vcc, v1, v0
	s_and_saveexec_b64 s[16:17], vcc
	s_cbranch_execz .LBB0_1123
	s_add_u32 s18, s70, 0x34e2300
	s_addc_u32 s19, s71, 0
	s_mov_b32 s3, 1
	s_mov_b64 s[22:23], 0
	v_mov_b32_e32 v1, 0
	s_branch .LBB0_1114

; DI unsigned xb_ld(unsigned* p)              { return __hip_atomic_load(p, __ATOMIC_RELAXED, __HIP_MEMORY_SCOPE_AGENT); }
; DI unsigned xb_add(unsigned* p, unsigned v) { return __hip_atomic_fetch_add(p, v, __ATOMIC_RELAXED, __HIP_MEMORY_SCOPE_AGENT); }
; #define XB_SPIN(cond, bar) do { unsigned _sp = 0; while (cond) { __builtin_amdgcn_s_sleep(1); \
;     if ((++_sp & 255u) == 0u) { if (xb_ld(&(bar)[XB_TMO])) break; if (_sp > XB_SPIN_CAP) { atomicAdd(&(bar)[XB_TMO], 1u); break; } } } } while (0)
; DI void xcd_barrier(unsigned* bar, volatile __attribute__((address_space(3))) unsigned* st) {
;     ...
;         const unsigned old = xb_add(&bar[XB_XSUB(x)], 1u);
;         const unsigned gen = old / nloc;
;         if (old + 1u == (gen + 1u) * nloc) {
;             __builtin_amdgcn_fence(__ATOMIC_RELEASE, "agent");
;             asm volatile("s_waitcnt vmcnt(0)" ::: "memory");
;             const unsigned og = xb_add(&bar[XB_TOP], 1u);
;             const unsigned tg = og / nx;
;             if (og + 1u == (tg + 1u) * nx) xb_add(&bar[XB_TOPGEN], 1u);
;             else XB_SPIN(xb_ld(&bar[XB_TOPGEN]) == tg, bar);
;             __builtin_amdgcn_fence(__ATOMIC_ACQUIRE, "agent");
;             xb_add(&bar[XB_XGEN(x)], 1u);
;             asm volatile("s_waitcnt vmcnt(0)" ::: "memory");
;         } else {
;             XB_SPIN(xb_ld(&bar[XB_XGEN(x)]) == gen, bar);
.LBB0_1169:
	s_or_b64 exec, exec, s[12:13]
	s_waitcnt vmcnt(0)
	v_readfirstlane_b32 s3, v3
	v_mul_u32_u24_e32 v2, 13, v2
	v_add_u32_e32 v5, s3, v0
	v_mov_b32_e32 v0, 12
	v_add_u32_e32 v3, 1, v5
	v_cmp_ne_u32_e32 vcc, v3, v2
	s_and_saveexec_b64 s[8:9], vcc
	s_xor_b64 s[8:9], exec, s[8:9]
	s_cbranch_execz .LBB0_1183
	buffer_inv sc1
	s_waitcnt lgkmcnt(0)
	v_mov_b32_e32 v1, 0x2000
	global_load_dword v1, v1, s[6:7] offset:1024 sc1
	s_add_u32 s16, s6, 0x2400
	s_addc_u32 s17, s7, 0
	s_waitcnt vmcnt(0)
	v_cmp_eq_u32_e32 vcc, v1, v0
	s_and_saveexec_b64 s[12:13], vcc
	s_cbranch_execz .LBB0_1182
	s_add_u32 s14, s70, 0x34e2300
	s_addc_u32 s15, s71, 0
	s_mov_b32 s3, 1
	s_mov_b64 s[18:19], 0
	v_mov_b32_e32 v1, 0
	s_branch .LBB0_1173

; DI unsigned xb_ld(unsigned* p)              { return __hip_atomic_load(p, __ATOMIC_RELAXED, __HIP_MEMORY_SCOPE_AGENT); }
; DI unsigned xb_add(unsigned* p, unsigned v) { return __hip_atomic_fetch_add(p, v, __ATOMIC_RELAXED, __HIP_MEMORY_SCOPE_AGENT); }
; #define XB_SPIN(cond, bar) do { unsigned _sp = 0; while (cond) { __builtin_amdgcn_s_sleep(1); \
;     if ((++_sp & 255u) == 0u) { if (xb_ld(&(bar)[XB_TMO])) break; if (_sp > XB_SPIN_CAP) { atomicAdd(&(bar)[XB_TMO], 1u); break; } } } } while (0)
; DI void xcd_barrier(unsigned* bar, volatile __attribute__((address_space(3))) unsigned* st) {
;     ...
;         const unsigned old = xb_add(&bar[XB_XSUB(x)], 1u);
;         const unsigned gen = old / nloc;
;         if (old + 1u == (gen + 1u) * nloc) {
;             __builtin_amdgcn_fence(__ATOMIC_RELEASE, "agent");
;             asm volatile("s_waitcnt vmcnt(0)" ::: "memory");
;             const unsigned og = xb_add(&bar[XB_TOP], 1u);
;             const unsigned tg = og / nx;
;             if (og + 1u == (tg + 1u) * nx) xb_add(&bar[XB_TOPGEN], 1u);
;             else XB_SPIN(xb_ld(&bar[XB_TOPGEN]) == tg, bar);
;             __builtin_amdgcn_fence(__ATOMIC_ACQUIRE, "agent");
;             xb_add(&bar[XB_XGEN(x)], 1u);
;             asm volatile("s_waitcnt vmcnt(0)" ::: "memory");
;         } else {
;             XB_SPIN(xb_ld(&bar[XB_XGEN(x)]) == gen, bar);
.LBB0_1249:
	s_or_b64 exec, exec, s[6:7]
	s_waitcnt vmcnt(0)
	v_readfirstlane_b32 s4, v3
	v_mul_u32_u24_e32 v2, 14, v2
	v_add_u32_e32 v5, s4, v0
	v_mov_b32_e32 v0, 13
	v_add_u32_e32 v3, 1, v5
	v_cmp_ne_u32_e32 vcc, v3, v2
	s_and_saveexec_b64 s[4:5], vcc
	s_xor_b64 s[4:5], exec, s[4:5]
	s_cbranch_execz .LBB0_1263
	buffer_inv sc1
	s_waitcnt lgkmcnt(0)
	v_mov_b32_e32 v1, 0x2000
	global_load_dword v1, v1, s[2:3] offset:1024 sc1
	s_add_u32 s10, s2, 0x2400
	s_addc_u32 s11, s3, 0
	s_waitcnt vmcnt(0)
	v_cmp_eq_u32_e32 vcc, v1, v0
	s_and_saveexec_b64 s[6:7], vcc
	s_cbranch_execz .LBB0_1262
	s_add_u32 s8, s70, 0x34e2300
	s_addc_u32 s9, s71, 0
	s_mov_b32 s22, 1
	s_mov_b64 s[12:13], 0
	v_mov_b32_e32 v1, 0
	s_branch .LBB0_1253
